# e45: e44 + all P1 transpose items on workgroups vcu>=160 (3 each, in the barrier slot); fold workgroups start their GEMM on a P0 raw/pool_w counter (write-through + counted) and wait for the barrier o
# baseline (speedup 1.0000x reference)
; #define LAS __attribute__((address_space(3)))
; #define SUB(i, ...) do { if (PROBE_PH == phk && PROBE_SUB == (i)) { __syncthreads(); tp0 = __builtin_amdgcn_s_memrealtime(); } __VA_ARGS__ if (PROBE_PH == phk && PROBE_SUB == (i)) { asm volatile("s_waitcnt vmcnt(0)" ::: "memory"); __syncthreads(); tp1 = __builtin_amdgcn_s_memrealtime(); } } while (0)
; __global__ void __launch_bounds__(NTHREADS, 2) mk_fwd(Args a) {
;     ...
;         SUB(0, if (bx < 192) gemv_item((LAS float*)lds, bx, a.in[1], a.in[3], a.in[4], a.in[5], (float*)(a.ws + WS_MOD));
;                else { const int b2 = bx - 192;
;                    transpose_dispatch((16 + b2) * 8 + wave, a.in[7], a.in[20], a.in[18], a.in[8], a.ws, scr, lane);
;                    if (b2 < 16) transpose_dispatch(b2 * 8 + wave, a.in[7], a.in[20], a.in[18], a.in[8], a.ws, scr, lane);
;                    for (int it = 80 + 3 * b2; it < 80 + 3 * b2 + 3; ++it) transpose_dispatch(it * 8 + wave, a.in[7], a.in[20], a.in[18], a.in[8], a.ws, scr, lane);
;                    if (b2 >= 16) transpose_dispatch((272 + b2 - 16) * 8 + wave, a.in[7], a.in[20], a.in[18], a.in[8], a.ws, scr, lane); } );
.LBB0_42:
	s_waitcnt vmcnt(0)
	s_barrier
	s_mov_b64 s[98:99], exec
	s_and_b64 exec, exec, s[82:83]
	s_cbranch_execz .Lp0_cnt
	v_mov_b32_e32 v2, 0xe000
	v_mov_b32_e32 v3, 1
	global_atomic_add v2, v3, s[50:51]
.Lp0_cnt:
	s_mov_b64 exec, s[98:99]
	s_add_u32 s10, s50, 0x1c00000
	s_addc_u32 s11, s51, 0
	s_mul_i32 s12, s8, 3
	s_add_u32 s8, s50, 0x1400000
	v_readlane_b32 s56, v254, 2
	s_addc_u32 s9, s51, 0
	v_readlane_b32 s70, v254, 16
	v_readlane_b32 s71, v254, 17
	s_add_u32 s6, s70, 0x1000
	v_lshrrev_b32_e32 v20, 3, v212
	v_and_b32_e32 v5, 7, v0
	s_addc_u32 s7, s71, 0
	v_lshlrev_b32_e32 v4, 2, v5
	v_lshlrev_b32_e32 v6, 4, v5
	v_lshlrev_b32_e32 v2, 3, v5
	v_mul_u32_u24_e32 v5, 0x420, v5
	v_lshlrev_b32_e32 v12, 2, v20
	s_add_u32 s4, s50, 0x800000
	v_add_u32_e32 v22, s1, v6
	v_add3_u32 v5, s1, v5, v12
	s_addc_u32 s5, s51, 0
	s_add_i32 s1, s12, 0x52
	s_mul_i32 s12, s16, 3
	s_add_i32 s18, s12, 0xfffffe0f
	s_mul_i32 s12, s16, 24
	v_mul_u32_u24_e32 v23, 0x84, v20
	s_add_i32 s12, s53, s12
	v_mov_b32_e32 v7, 0
	s_add_i32 s19, s12, 0xfffff080
	v_add_u32_e32 v22, v22, v23
	v_lshl_add_u64 v[8:9], s[40:41], 0, v[6:7]
	v_or_b32_e32 v21, 8, v20
	v_or_b32_e32 v3, 16, v20
	v_or_b32_e32 v1, 24, v20
	v_lshl_add_u64 v[10:11], s[10:11], 0, v[6:7]
	v_lshl_add_u64 v[12:13], s[44:45], 0, v[6:7]
	v_lshl_add_u64 v[14:15], s[8:9], 0, v[6:7]
	v_lshl_add_u64 v[16:17], s[6:7], 0, v[6:7]
	v_lshl_add_u64 v[18:19], s[4:5], 0, v[6:7]
	s_lshl_b32 s20, s19, 5
	s_mov_b32 s13, 0
	v_add_u32_e32 v23, 0x420, v22
	v_add_u32_e32 v24, 0x428, v22
	v_add_u32_e32 v25, 0x840, v22
	v_add_u32_e32 v26, 0x848, v22
	v_add_u32_e32 v27, 0xc60, v22
	v_add_u32_e32 v28, 0xc68, v22
	v_add_u32_e32 v29, 0x1080, v22
	v_add_u32_e32 v30, 0x1088, v22
	v_add_u32_e32 v31, 0x14a0, v22
	v_add_u32_e32 v32, 0x14a8, v22
	v_add_u32_e32 v33, 0x18c0, v22
	v_add_u32_e32 v34, 0x18c8, v22
	v_add_u32_e32 v35, 0x1ce0, v22
	v_add_u32_e32 v36, 0x1ce8, v22
	s_mov_b32 s21, 0x20000
	s_mov_b32 s22, 0x40000
	s_mov_b32 s23, 0x60000
	s_mov_b32 s24, 0x80000
	s_mov_b32 s25, 0xa0000
	s_mov_b32 s26, 0xc0000
	s_mov_b32 s27, 0xe0000
	v_readlane_b32 s57, v254, 3
	v_readlane_b32 s58, v254, 4
	v_readlane_b32 s59, v254, 5
	v_readlane_b32 s60, v254, 6
	v_readlane_b32 s61, v254, 7
	v_readlane_b32 s62, v254, 8
	v_readlane_b32 s63, v254, 9
	v_readlane_b32 s64, v254, 10
	v_readlane_b32 s65, v254, 11
	v_readlane_b32 s66, v254, 12
	v_readlane_b32 s67, v254, 13
	v_readlane_b32 s68, v254, 14
	v_readlane_b32 s69, v254, 15
	s_branch .LBB0_44

; #define SUB(i, ...) do { if (PROBE_PH == phk && PROBE_SUB == (i)) { __syncthreads(); tp0 = __builtin_amdgcn_s_memrealtime(); } __VA_ARGS__ if (PROBE_PH == phk && PROBE_SUB == (i)) { asm volatile("s_waitcnt vmcnt(0)" ::: "memory"); __syncthreads(); tp1 = __builtin_amdgcn_s_memrealtime(); } } while (0)
; __global__ void __launch_bounds__(NTHREADS, 2) mk_fwd(Args a) {
;     ...
;         { pg8::ListOrder S; S.init(32, 1, 8, G, vcu >= 128 && vcu < 160 ? vcu - 128 : 1 << 20);
;           EpiWp E{(f16*)(a.ws + WS_WIN)};
;           SUB(3, pg8::gemm_phase<CfgWp, EpiWp, pg8::ListOrder, true, true>(lds, (const char*)(a.ws + WS_WPOOL), (const char*)(a.ws + WS_WRAW), S, E); ); }
;     ...
;         SUB(2, if (vcu < 128) transpose_dispatch((320 + vcu) * 8 + wave, a.in[7], a.in[20], a.in[18], a.in[8], a.ws, scr, lane);
;                else { const int b2 = vcu - 128;
;                    for (int it = 448 + 3 * b2; it < 448 + 3 * b2 + 3; ++it) transpose_dispatch(it * 8 + wave, a.in[7], a.in[20], a.in[18], a.in[8], a.ws, scr, lane);
;                    if (b2 < 16) transpose_dispatch((832 + b2) * 8 + wave, a.in[7], a.in[20], a.in[18], a.in[8], a.ws, scr, lane); } );
.LBB0_132:
	s_cmp_lt_i32 s78, 2
	s_cselect_b64 s[0:1], -1, 0
	s_and_b64 s[76:77], s[0:1], s[4:5]
	s_andn2_b64 vcc, exec, s[76:77]
	s_cbranch_vccnz .LBB0_230
	s_mov_b32 s100, 0
	s_cmpk_gt_i32 s81, 0x7f
	s_cselect_b64 s[18:19], -1, 0
	s_cmpk_lt_i32 s81, 0x80
	s_cbranch_scc1 .LBB0_135
	v_and_b32_e32 v22, 15, v0
	v_lshrrev_b32_e32 v1, 1, v0
	s_cmpk_lt_i32 s81, 0xa0
	s_cbranch_scc1 .Lp1_fold_wg
	s_mov_b32 s100, 1
	s_mov_b32 s99, 0
.Lp1_items:
	s_add_u32 s0, s50, 0x2000000
	s_addc_u32 s1, s51, 0
	s_add_u32 s4, s50, 0x13600000
	s_addc_u32 s5, s51, 0
	s_mul_i32 s28, s53, 0x2100
	s_mov_b32 s13, 0
	s_sub_i32 s6, s81, 0xa0
	s_mul_i32 s6, s6, 3
	s_add_i32 s6, s6, s99
	s_cmp_gt_u32 s6, 283
	s_cbranch_scc1 .Lp1_items_done
	s_add_i32 s7, s6, 320
	s_cmp_lt_u32 s6, 146
	s_cbranch_scc1 .Lp1_item_go
	s_mul_i32 s7, s6, 3
	s_add_i32 s7, s7, 30
	s_cmp_lt_u32 s6, 268
	s_cbranch_scc1 .Lp1_item_go
	s_add_i32 s7, s6, 564
.Lp1_item_go:
	s_sub_i32 s6, s7, 320
	s_lshl_b32 s6, s6, 3
	s_add_i32 s6, s6, s53
	s_mov_b64 s[2:3], -1
	s_branch .LBB0_213
.Lp1_fold_wg:
	s_and_saveexec_b64 s[2:3], s[82:83]
	s_cbranch_execz .Lp1_cnt_done
	v_mov_b32_e32 v2, 0xe000
	s_mov_b32 s101, 0
.Lp1_cnt:
	global_load_dword v3, v2, s[50:51] sc1
	s_add_u32 s101, s101, 1
	s_waitcnt vmcnt(0)
	v_readfirstlane_b32 vcc_lo, v3
	s_cmp_ge_u32 vcc_lo, 64
	s_cbranch_scc1 .Lp1_cnt_polled
	s_cmp_gt_u32 s101, 0x4000
	s_cbranch_scc1 .Lp1_cnt_polled
	s_sleep 1
	s_branch .Lp1_cnt

; #define SUB(i, ...) do { if (PROBE_PH == phk && PROBE_SUB == (i)) { __syncthreads(); tp0 = __builtin_amdgcn_s_memrealtime(); } __VA_ARGS__ if (PROBE_PH == phk && PROBE_SUB == (i)) { asm volatile("s_waitcnt vmcnt(0)" ::: "memory"); __syncthreads(); tp1 = __builtin_amdgcn_s_memrealtime(); } } while (0)
; __global__ void __launch_bounds__(NTHREADS, 2) mk_fwd(Args a) {
;     ...
;         { pg8::ListOrder S; S.init(32, 1, 8, G, vcu >= 128 && vcu < 160 ? vcu - 128 : 1 << 20);
;           EpiWp E{(f16*)(a.ws + WS_WIN)};
;           SUB(3, pg8::gemm_phase<CfgWp, EpiWp, pg8::ListOrder, true, true>(lds, (const char*)(a.ws + WS_WPOOL), (const char*)(a.ws + WS_WRAW), S, E); ); }
.Lp1_cnt_done:
	s_or_b64 exec, exec, s[2:3]
	s_waitcnt lgkmcnt(0)
	s_barrier
	s_mov_b32 s100, 3
	s_branch .LBB0_165

; #define SUB(i, ...) do { if (PROBE_PH == phk && PROBE_SUB == (i)) { __syncthreads(); tp0 = __builtin_amdgcn_s_memrealtime(); } __VA_ARGS__ if (PROBE_PH == phk && PROBE_SUB == (i)) { asm volatile("s_waitcnt vmcnt(0)" ::: "memory"); __syncthreads(); tp1 = __builtin_amdgcn_s_memrealtime(); } } while (0)
; __global__ void __launch_bounds__(NTHREADS, 2) mk_fwd(Args a) {
;     ...
;         { pg8::ListOrder S; S.init(32, 1, 8, G, vcu >= 128 && vcu < 160 ? vcu - 128 : 1 << 20);
;           EpiWp E{(f16*)(a.ws + WS_WIN)};
;           SUB(3, pg8::gemm_phase<CfgWp, EpiWp, pg8::ListOrder, true, true>(lds, (const char*)(a.ws + WS_WPOOL), (const char*)(a.ws + WS_WRAW), S, E); ); }
.LBB0_165:
	s_cmp_eq_u32 s100, 3
	s_cbranch_scc1 .Lp1_skipw
	s_and_saveexec_b64 s[2:3], s[82:83]
	s_cbranch_execz .Lp1_waited
	v_mov_b32_e32 v2, 0x3500
	s_mov_b32 s0, 0

; #define SUB(i, ...) do { if (PROBE_PH == phk && PROBE_SUB == (i)) { __syncthreads(); tp0 = __builtin_amdgcn_s_memrealtime(); } __VA_ARGS__ if (PROBE_PH == phk && PROBE_SUB == (i)) { asm volatile("s_waitcnt vmcnt(0)" ::: "memory"); __syncthreads(); tp1 = __builtin_amdgcn_s_memrealtime(); } } while (0)
; __global__ void __launch_bounds__(NTHREADS, 2) mk_fwd(Args a) {
;     ...
;           SUB(3, pg8::gemm_phase<CfgWp, EpiWp, pg8::ListOrder, true, true>(lds, (const char*)(a.ws + WS_WPOOL), (const char*)(a.ws + WS_WRAW), S, E); ); }
;         SUB(1, norm_rows(vcu * NWAVES + wave, lane, a.in[0], a.in[2], a.in[6], (const float*)(a.ws + WS_MOD), (f16*)(a.ws + WS_H)); );
.LBB0_178:
	s_waitcnt vmcnt(0)
	v_readlane_b32 s76, v254, 36
	v_readlane_b32 s18, v254, 34
	s_mov_b32 s81, s52
	s_mov_b64 s[78:79], s[56:57]
	s_mov_b32 s52, s64
	s_mov_b64 s[82:83], s[66:67]
	v_readlane_b32 s77, v254, 37
	v_readlane_b32 s19, v254, 35
	s_mov_b32 s20, s65
	s_barrier
	s_cmp_eq_u32 s100, 3
	s_cbranch_scc0 .Lp1_nw2
	s_and_saveexec_b64 s[2:3], s[82:83]
	s_cbranch_execz .Lp1_w2_done
	v_mov_b32_e32 v2, 0x3500
	s_mov_b32 s101, 0
.Lp1_w2:
	global_load_dword v3, v2, s[50:51] sc1
	s_add_u32 s101, s101, 1
	s_waitcnt vmcnt(0)
	v_readfirstlane_b32 vcc_lo, v3
	s_cmp_lg_u32 vcc_lo, 0
	s_cbranch_scc1 .Lp1_w2_polled
	s_cmp_gt_u32 s101, 0x4000
	s_cbranch_scc1 .Lp1_w2_polled
	s_sleep 1
	s_branch .Lp1_w2

; __device__ __forceinline__ f32x4 ld_nt(const float* p) { return __builtin_nontemporal_load((const f32x4*)p); }
; __device__ __forceinline__ void norm_rows(int gw, int lane, const float* x, const float* ctx, const float* ng, const float* mod, f16* h) {
;     f32x4 gs[8], sh[8];
;     auto load_mod = [&](int mr) { const float* shp = mod + mr * 3 * D;
; #pragma unroll
;         for (int j = 0; j < 8; ++j) { const int cidx = 256 * j + 4 * lane; const f32x4 g4 = *(const f32x4*)(ng + cidx), s4 = *(const f32x4*)(shp + D + cidx); gs[j] = g4 * (1.f + s4); sh[j] = *(const f32x4*)(shp + cidx); } };
;     auto finish_row = [&](const f32x4 (&v)[8], f16* dst) { float ss = 0.f;
; #pragma unroll
;         for (int j = 0; j < 8; ++j) ss += (v[j][0] * v[j][0] + v[j][1] * v[j][1]) + (v[j][2] * v[j][2] + v[j][3] * v[j][3]);
;         const float rstd = rsqrtf(wave_sum(ss) * (1.f / D) + EPS);
; #pragma unroll
;         for (int j = 0; j < 8; ++j) { const f32x4 o = v[j] * rstd * gs[j] + sh[j]; u32x2 w; w.x = pk_f16(o[0], o[1]); w.y = pk_f16(o[2], o[3]); *(u32x2*)(dst + 256 * j + 4 * lane) = w; } };
;     constexpr int RPW = 8;
;     const int r0 = gw * RPW;
;     if (r0 < M_LAT) { load_mod(r0 / SEQ);
; #pragma unroll 1
;         for (int rb = r0; rb < r0 + RPW; rb += 4) { f32x4 v[4][8];
; #pragma unroll
;             for (int rr = 0; rr < 4; ++rr)
; #pragma unroll
;                 for (int j = 0; j < 8; ++j) v[rr][j] = ld_nt(x + (size_t)(rb + rr) * D + 256 * j + 4 * lane);
;             __builtin_amdgcn_sched_barrier(0);
; #pragma unroll
;             for (int rr = 0; rr < 4; ++rr) finish_row(v[rr], h + (size_t)(rb + rr) * D); } }
.Lp1_w2_done:
	s_or_b64 exec, exec, s[2:3]
	s_waitcnt lgkmcnt(0)
	s_barrier
	s_mov_b32 s100, 2
.Lp1_nw2:
.LBB0_179:
	s_lshl_b32 s2, s81, 3
	s_add_i32 s6, s2, s53
	s_cmpk_gt_i32 s6, 0x7ff
	v_lshlrev_b32_e32 v162, 4, v212
	s_cbranch_scc1 .LBB0_182
	s_ashr_i32 s2, s6, 31
	s_lshr_b32 s2, s2, 22
	s_add_i32 s2, s6, s2
	s_lshr_b32 s2, s2, 10
	s_mulk_i32 s2, 0x1800
	s_ashr_i32 s3, s2, 31
	s_lshl_b32 s12, s6, 3
	s_lshl_b64 s[2:3], s[2:3], 2
	s_add_u32 s7, s50, s2
	s_addc_u32 s8, s51, s3
	s_add_u32 s2, s7, 0x100000
	s_addc_u32 s3, s8, 0
	s_add_u32 s10, s7, 0x102000
	s_addc_u32 s11, s8, 0
	global_load_dwordx4 v[34:37], v162, s[10:11]
	v_mbcnt_lo_u32_b32 v2, -1, 0
	v_or_b32_e32 v1, 0x400, v162
	v_or_b32_e32 v22, 0x1400, v162
	v_mbcnt_hi_u32_b32 v98, -1, v2
	global_load_dwordx4 v[38:41], v1, s[10:11]
	global_load_dwordx4 v[54:57], v22, s[10:11]
	v_or_b32_e32 v1, 0x800, v162
	v_or_b32_e32 v26, 0x1800, v162
	v_and_b32_e32 v2, 64, v98
	global_load_dwordx4 v[42:45], v1, s[10:11]
	global_load_dwordx4 v[58:61], v26, s[10:11]
	v_or_b32_e32 v1, 0xc00, v162
	v_or_b32_e32 v30, 0x1c00, v162
	v_readlane_b32 s56, v254, 2
	v_xor_b32_e32 v3, 1, v98
	v_add_u32_e32 v101, 64, v2
	global_load_dwordx4 v[46:49], v1, s[10:11]
	global_load_dwordx4 v[62:65], v30, s[10:11]
	v_or_b32_e32 v1, 0x1000, v162
	v_readlane_b32 s68, v254, 14
	v_readlane_b32 s69, v254, 15
	v_xor_b32_e32 v4, 2, v98
	v_cmp_lt_i32_e32 vcc, v3, v101
	global_load_dwordx4 v[50:53], v1, s[10:11]
	s_nop 1
	global_load_dwordx4 v[66:69], v162, s[68:69]
	global_load_dwordx4 v[70:73], v162, s[68:69] offset:1024
	global_load_dwordx4 v[74:77], v162, s[68:69] offset:2048
	global_load_dwordx4 v[78:81], v162, s[68:69] offset:3072
	global_load_dwordx4 v[82:85], v1, s[68:69]
	global_load_dwordx4 v[86:89], v22, s[68:69]
	global_load_dwordx4 v[90:93], v26, s[68:69]
	global_load_dwordx4 v[94:97], v30, s[68:69]
	v_cndmask_b32_e32 v102, v98, v3, vcc
	v_cmp_lt_i32_e32 vcc, v4, v101
	v_xor_b32_e32 v99, 4, v98
	v_xor_b32_e32 v100, 8, v98
	v_cndmask_b32_e32 v103, v98, v4, vcc
	global_load_dwordx4 v[2:5], v162, s[2:3]
	global_load_dwordx4 v[6:9], v162, s[2:3] offset:1024
	global_load_dwordx4 v[10:13], v162, s[2:3] offset:2048
	global_load_dwordx4 v[14:17], v162, s[2:3] offset:3072
	global_load_dwordx4 v[18:21], v1, s[2:3]
	s_nop 0
	global_load_dwordx4 v[22:25], v22, s[2:3]
	s_nop 0
	global_load_dwordx4 v[26:29], v26, s[2:3]
	s_nop 0
	global_load_dwordx4 v[30:33], v30, s[2:3]
	v_cmp_lt_i32_e32 vcc, v99, v101
	s_lshl_b32 s2, s81, 6
	s_lshl_b32 s3, s53, 3
	v_cndmask_b32_e32 v99, v98, v99, vcc
	v_cmp_lt_i32_e32 vcc, v100, v101
	s_add_i32 s2, s2, s3
	s_ashr_i32 s13, s12, 31
	s_add_i32 s7, s2, -4
	s_lshl_b64 s[2:3], s[12:13], 12
	s_add_u32 s2, s50, s2
	s_addc_u32 s3, s51, s3
	v_readlane_b32 s57, v254, 3
	v_lshlrev_b32_e32 v1, 2, v102
	v_lshlrev_b32_e32 v202, 2, v103
	v_lshlrev_b32_e32 v203, 2, v99
	s_movk_i32 s10, 0xd000
	s_movk_i32 s11, 0xe000
	s_mov_b32 s14, 0x3a000000
	s_mov_b32 s22, 0x358637bd
	s_mov_b32 s15, 0x800000
	s_mov_b64 s[24:25], 0x4000
	s_mov_b64 s[26:27], 0x8000
	v_readlane_b32 s58, v254, 4
	v_readlane_b32 s59, v254, 5
	v_readlane_b32 s60, v254, 6
	v_readlane_b32 s61, v254, 7
	v_readlane_b32 s62, v254, 8
	v_readlane_b32 s63, v254, 9
	v_readlane_b32 s64, v254, 10
	v_readlane_b32 s65, v254, 11
	v_readlane_b32 s66, v254, 12
	v_readlane_b32 s67, v254, 13
	v_readlane_b32 s70, v254, 16
	v_readlane_b32 s71, v254, 17
	s_waitcnt vmcnt(0)
	v_pk_add_f32 v[34:35], v[34:35], 1.0 op_sel_hi:[1,0]
	v_pk_add_f32 v[36:37], v[36:37], 1.0 op_sel_hi:[1,0]
	v_pk_add_f32 v[40:41], v[40:41], 1.0 op_sel_hi:[1,0]
	v_pk_add_f32 v[38:39], v[38:39], 1.0 op_sel_hi:[1,0]
	v_pk_add_f32 v[56:57], v[56:57], 1.0 op_sel_hi:[1,0]
	v_pk_add_f32 v[54:55], v[54:55], 1.0 op_sel_hi:[1,0]
	v_pk_add_f32 v[44:45], v[44:45], 1.0 op_sel_hi:[1,0]
	v_pk_add_f32 v[42:43], v[42:43], 1.0 op_sel_hi:[1,0]
	v_pk_add_f32 v[60:61], v[60:61], 1.0 op_sel_hi:[1,0]
	v_pk_add_f32 v[58:59], v[58:59], 1.0 op_sel_hi:[1,0]
	v_pk_add_f32 v[48:49], v[48:49], 1.0 op_sel_hi:[1,0]
	v_pk_mul_f32 v[166:167], v[66:67], v[34:35]
	v_cndmask_b32_e32 v34, v98, v100, vcc
	v_lshlrev_b32_e32 v204, 2, v34
	v_xor_b32_e32 v34, 16, v98
	v_cmp_lt_i32_e32 vcc, v34, v101
	v_mov_b32_e32 v35, 0
	v_pk_mul_f32 v[164:165], v[68:69], v[36:37]
	v_cndmask_b32_e32 v34, v98, v34, vcc
	v_lshlrev_b32_e32 v205, 2, v34
	v_xor_b32_e32 v34, 32, v98
	v_cmp_lt_i32_e32 vcc, v34, v101
	v_mov_b32_e32 v163, v35
	v_pk_add_f32 v[46:47], v[46:47], 1.0 op_sel_hi:[1,0]
	v_cndmask_b32_e32 v34, v98, v34, vcc
	v_lshlrev_b32_e32 v206, 2, v34
	v_lshlrev_b32_e32 v34, 3, v212
	v_lshl_add_u64 v[36:37], s[2:3], 0, v[34:35]
	s_mov_b64 s[2:3], 0x6103e00
	v_lshl_add_u64 v[196:197], v[36:37], 0, s[2:3]
	s_lshl_b64 s[2:3], s[12:13], 13
	s_add_u32 s2, s56, s2
	s_addc_u32 s3, s57, s3
	v_pk_add_f32 v[52:53], v[52:53], 1.0 op_sel_hi:[1,0]
	v_pk_add_f32 v[50:51], v[50:51], 1.0 op_sel_hi:[1,0]
	v_pk_add_f32 v[64:65], v[64:65], 1.0 op_sel_hi:[1,0]
	v_pk_add_f32 v[62:63], v[62:63], 1.0 op_sel_hi:[1,0]
	v_lshl_add_u64 v[34:35], s[2:3], 0, v[162:163]
	s_mov_b64 s[2:3], 0x7c00
	v_pk_mul_f32 v[168:169], v[72:73], v[40:41]
	v_pk_mul_f32 v[170:171], v[70:71], v[38:39]
	v_pk_mul_f32 v[172:173], v[76:77], v[44:45]
	v_pk_mul_f32 v[174:175], v[74:75], v[42:43]
	v_pk_mul_f32 v[176:177], v[80:81], v[48:49]
	v_pk_mul_f32 v[178:179], v[78:79], v[46:47]
	v_pk_mul_f32 v[180:181], v[84:85], v[52:53]
	v_pk_mul_f32 v[182:183], v[82:83], v[50:51]
	v_pk_mul_f32 v[184:185], v[88:89], v[56:57]
	v_pk_mul_f32 v[186:187], v[86:87], v[54:55]
	v_pk_mul_f32 v[188:189], v[92:93], v[60:61]
	v_pk_mul_f32 v[190:191], v[90:91], v[58:59]
	v_pk_mul_f32 v[192:193], v[96:97], v[64:65]
	v_pk_mul_f32 v[194:195], v[94:95], v[62:63]
	v_lshl_add_u64 v[198:199], v[34:35], 0, s[2:3]
	s_movk_i32 s13, 0xf000

; #define SUB(i, ...) do { if (PROBE_PH == phk && PROBE_SUB == (i)) { __syncthreads(); tp0 = __builtin_amdgcn_s_memrealtime(); } __VA_ARGS__ if (PROBE_PH == phk && PROBE_SUB == (i)) { asm volatile("s_waitcnt vmcnt(0)" ::: "memory"); __syncthreads(); tp1 = __builtin_amdgcn_s_memrealtime(); } } while (0)
; __global__ void __launch_bounds__(NTHREADS, 2) mk_fwd(Args a) {
;     ...
;         SUB(2, if (vcu < 128) transpose_dispatch((320 + vcu) * 8 + wave, a.in[7], a.in[20], a.in[18], a.in[8], a.ws, scr, lane);
;                else { const int b2 = vcu - 128;
;                    for (int it = 448 + 3 * b2; it < 448 + 3 * b2 + 3; ++it) transpose_dispatch(it * 8 + wave, a.in[7], a.in[20], a.in[18], a.in[8], a.ws, scr, lane);
;                    if (b2 < 16) transpose_dispatch((832 + b2) * 8 + wave, a.in[7], a.in[20], a.in[18], a.in[8], a.ws, scr, lane); } );
.LBB0_230:
	s_cmp_eq_u32 s100, 1
	s_cbranch_scc0 .Lp1_seam
	s_add_i32 s99, s99, 1
	s_cmp_lt_u32 s99, 3
	s_cbranch_scc1 .Lp1_items
.Lp1_items_done:
	s_mov_b32 s99, 0
	s_mov_b32 s100, 2
	v_and_b32_e32 v22, 15, v0
	v_lshrrev_b32_e32 v1, 1, v0
	s_cmpk_gt_i32 s81, 0x7f
	s_cselect_b64 s[18:19], -1, 0
	s_branch .LBB0_165
